# v15 plus prep items rebalanced: blocks 0..383 one R item each, blocks 384..511 three T items each
# speedup vs baseline: 1.0062x; 1.0014x over previous
.LBB0_279:
	v_readlane_b32 s51, v239, 20
	v_readlane_b32 s98, v243, 0
	s_cmpk_gt_i32 s98, 0x17f
	s_movk_i32 s99, 0x300
	s_cselect_b32 s98, 0x80, s99
	s_cmpk_eq_i32 s51, 0x200
	s_cselect_b32 s98, s98, s51
	s_add_i32 s56, s56, s98
	s_cmpk_gt_i32 s56, 0x2ff
	s_waitcnt vmcnt(0)
	s_barrier
	s_cbranch_scc1 .LBB0_571
